# adaLN matvec loop processes two 16-row weight blocks per iteration (32 loads in flight per wait)
# baseline (speedup 1.0000x reference)
.LBB0_13:
	v_add_co_u32_e64 v14, s[4:5], s15, v8
	v_add_co_u32_e32 v10, vcc, 0xfffd0000, v8
	s_nop 0
	v_addc_co_u32_e64 v15, s[4:5], -1, v9, s[4:5]
	v_add_co_u32_e64 v16, s[4:5], s16, v8
	v_addc_co_u32_e32 v11, vcc, -1, v9, vcc
	s_nop 0
	v_addc_co_u32_e64 v17, s[4:5], -1, v9, s[4:5]
	v_add_co_u32_e64 v18, s[4:5], s17, v8
	global_load_dword v12, v[8:9], off
	s_nop 0
	v_addc_co_u32_e64 v19, s[4:5], -1, v9, s[4:5]
	v_add_co_u32_e64 v20, s[4:5], s18, v8
	v_add_u32_e32 v13, s39, v7
	s_nop 0
	v_addc_co_u32_e64 v21, s[4:5], -1, v9, s[4:5]
	v_add_co_u32_e64 v24, s[4:5], s19, v8
	v_add_u32_e32 v23, 0x11000, v13
	s_nop 0
	v_addc_co_u32_e64 v25, s[4:5], -1, v9, s[4:5]
	v_add_co_u32_e64 v26, s[4:5], s22, v8
	v_add_u32_e32 v44, 0x12000, v13
	s_nop 0
	v_addc_co_u32_e64 v27, s[4:5], -1, v9, s[4:5]
	v_add_co_u32_e64 v28, s[4:5], s23, v8
	v_add_u32_e32 v45, 0x13000, v13
	s_nop 0
	v_addc_co_u32_e64 v29, s[4:5], -1, v9, s[4:5]
	v_add_co_u32_e64 v30, s[4:5], s13, v8
	global_load_dword v80, v[14:15], off
	global_load_dword v82, v[16:17], off
	global_load_dword v84, v[18:19], off
	global_load_dword v86, v[20:21], off
	global_load_dword v88, v[24:25], off
	global_load_dword v90, v[26:27], off
	global_load_dword v92, v[28:29], off
	v_addc_co_u32_e64 v31, s[4:5], 0, v9, s[4:5]
	v_add_co_u32_e64 v32, s[4:5], s24, v8
	v_add_u32_e32 v46, 0x14000, v13
	s_nop 0
	v_addc_co_u32_e64 v33, s[4:5], 0, v9, s[4:5]
	v_add_co_u32_e64 v34, s[4:5], s14, v8
	v_add_u32_e32 v47, 0x11010, v13
	s_nop 0
	v_addc_co_u32_e64 v35, s[4:5], 0, v9, s[4:5]
	v_add_co_u32_e64 v36, s[4:5], s25, v8
	v_add_u32_e32 v48, 0x12010, v13
	s_nop 0
	v_addc_co_u32_e64 v37, s[4:5], 0, v9, s[4:5]
	v_add_co_u32_e64 v38, s[4:5], s36, v8
	global_load_dword v94, v[30:31], off
	global_load_dword v96, v[32:33], off
	global_load_dword v98, v[34:35], off
	global_load_dword v100, v[36:37], off
	v_addc_co_u32_e64 v39, s[4:5], 0, v9, s[4:5]
	v_add_co_u32_e64 v40, s[4:5], s37, v8
	v_add_u32_e32 v49, 0x13010, v13
	s_nop 0
	v_addc_co_u32_e64 v41, s[4:5], 0, v9, s[4:5]
	v_add_co_u32_e64 v42, s[4:5], s38, v8
	v_add_u32_e32 v50, 0x14010, v13
	s_nop 0
	v_addc_co_u32_e64 v43, s[4:5], 0, v9, s[4:5]
	global_load_dword v102, v[38:39], off
	global_load_dword v104, v[40:41], off
	global_load_dword v106, v[42:43], off
	v_add_u32_e32 v51, 0x11020, v13
	global_load_dword v10, v[10:11], off
	v_add_u32_e32 v52, 0x12020, v13
	v_add_u32_e32 v56, 0x13020, v13
	v_add_u32_e32 v60, 0x14020, v13
	v_add_u32_e32 v64, 0x11030, v13
	v_add_u32_e32 v68, 0x12030, v13
	v_add_u32_e32 v72, 0x13030, v13
	v_add_u32_e32 v13, 0x14030, v13
	ds_read_b128 v[14:17], v23
	ds_read_b128 v[18:21], v44
	ds_read_b128 v[24:27], v45
	ds_read_b128 v[28:31], v46
	ds_read_b128 v[32:35], v47
	ds_read_b128 v[36:39], v48
	ds_read_b128 v[40:43], v49
	ds_read_b128 v[44:47], v50
	ds_read_b128 v[48:51], v51
	ds_read_b128 v[52:55], v52
	ds_read_b128 v[56:59], v56
	ds_read_b128 v[60:63], v60
	ds_read_b128 v[64:67], v64
	ds_read_b128 v[68:71], v68
	ds_read_b128 v[72:75], v72
	ds_read_b128 v[76:79], v13
	s_waitcnt lgkmcnt(14)
	v_mov_b32_e32 v108, v14
	v_mov_b32_e32 v109, v18
	s_waitcnt lgkmcnt(13)
	v_mov_b32_e32 v110, v24
	s_waitcnt lgkmcnt(12)
	v_mov_b32_e32 v111, v28
	v_mov_b32_e32 v18, v15
	v_mov_b32_e32 v28, v25
	v_mov_b32_e32 v14, v16
	v_mov_b32_e32 v15, v20
	v_mov_b32_e32 v20, v17
	v_mov_b32_e32 v16, v26
	v_mov_b32_e32 v17, v30
	v_mov_b32_e32 v30, v27
	s_waitcnt lgkmcnt(11)
	v_mov_b32_e32 v24, v32
	s_waitcnt lgkmcnt(10)
	v_mov_b32_e32 v25, v36
	v_mov_b32_e32 v36, v33
	s_waitcnt lgkmcnt(9)
	v_mov_b32_e32 v32, v40
	s_waitcnt lgkmcnt(8)
	v_mov_b32_e32 v33, v44
	v_mov_b32_e32 v44, v41
	v_mov_b32_e32 v26, v34
	v_mov_b32_e32 v27, v38
	v_mov_b32_e32 v38, v35
	v_mov_b32_e32 v34, v42
	v_mov_b32_e32 v35, v46
	v_mov_b32_e32 v46, v43
	s_waitcnt lgkmcnt(7)
	v_mov_b32_e32 v40, v48
	s_waitcnt lgkmcnt(6)
	v_mov_b32_e32 v41, v52
	v_mov_b32_e32 v52, v49
	s_waitcnt lgkmcnt(5)
	v_mov_b32_e32 v48, v56
	s_waitcnt lgkmcnt(4)
	v_mov_b32_e32 v49, v60
	v_mov_b32_e32 v60, v57
	v_mov_b32_e32 v42, v50
	v_mov_b32_e32 v43, v54
	v_mov_b32_e32 v54, v51
	v_mov_b32_e32 v50, v58
	v_mov_b32_e32 v51, v62
	v_mov_b32_e32 v62, v59
	s_waitcnt lgkmcnt(3)
	v_mov_b32_e32 v56, v64
	s_waitcnt lgkmcnt(2)
	v_mov_b32_e32 v57, v68
	v_mov_b32_e32 v68, v65
	s_waitcnt lgkmcnt(1)
	v_mov_b32_e32 v64, v72
	s_waitcnt lgkmcnt(0)
	v_mov_b32_e32 v65, v76
	v_mov_b32_e32 v76, v73
	v_mov_b32_e32 v58, v66
	v_mov_b32_e32 v59, v70
	v_mov_b32_e32 v70, v67
	v_mov_b32_e32 v66, v74
	v_mov_b32_e32 v67, v78
	s_add_i32 s39, s39, 64
	v_mov_b32_e32 v78, v75
	v_lshl_add_u64 v[8:9], v[8:9], 0, s[10:11]
	v_add_co_u32_e64 v116, s[4:5], s15, v8
	v_add_co_u32_e32 v112, vcc, 0xfffd0000, v8
	s_nop 0
	v_addc_co_u32_e64 v117, s[4:5], -1, v9, s[4:5]
	v_add_co_u32_e64 v118, s[4:5], s16, v8
	v_addc_co_u32_e32 v113, vcc, -1, v9, vcc
	s_nop 0
	v_addc_co_u32_e64 v119, s[4:5], -1, v9, s[4:5]
	v_add_co_u32_e64 v120, s[4:5], s17, v8
	global_load_dword v114, v[8:9], off
	s_nop 0
	v_addc_co_u32_e64 v121, s[4:5], -1, v9, s[4:5]
	v_add_co_u32_e64 v122, s[4:5], s18, v8
	v_add_u32_e32 v115, s39, v7
	s_nop 0
	v_addc_co_u32_e64 v123, s[4:5], -1, v9, s[4:5]
	v_add_co_u32_e64 v126, s[4:5], s19, v8
	v_add_u32_e32 v125, 0x11000, v115
	s_nop 0
	v_addc_co_u32_e64 v127, s[4:5], -1, v9, s[4:5]
	v_add_co_u32_e64 v128, s[4:5], s22, v8
	v_add_u32_e32 v146, 0x12000, v115
	s_nop 0
	v_addc_co_u32_e64 v129, s[4:5], -1, v9, s[4:5]
	v_add_co_u32_e64 v130, s[4:5], s23, v8
	v_add_u32_e32 v147, 0x13000, v115
	s_nop 0
	v_addc_co_u32_e64 v131, s[4:5], -1, v9, s[4:5]
	v_add_co_u32_e64 v132, s[4:5], s13, v8
	global_load_dword v182, v[116:117], off
	global_load_dword v184, v[118:119], off
	global_load_dword v186, v[120:121], off
	global_load_dword v188, v[122:123], off
	global_load_dword v190, v[126:127], off
	global_load_dword v192, v[128:129], off
	global_load_dword v194, v[130:131], off
	v_addc_co_u32_e64 v133, s[4:5], 0, v9, s[4:5]
	v_add_co_u32_e64 v134, s[4:5], s24, v8
	v_add_u32_e32 v148, 0x14000, v115
	s_nop 0
	v_addc_co_u32_e64 v135, s[4:5], 0, v9, s[4:5]
	v_add_co_u32_e64 v136, s[4:5], s14, v8
	v_add_u32_e32 v149, 0x11010, v115
	s_nop 0
	v_addc_co_u32_e64 v137, s[4:5], 0, v9, s[4:5]
	v_add_co_u32_e64 v138, s[4:5], s25, v8
	v_add_u32_e32 v150, 0x12010, v115
	s_nop 0
	v_addc_co_u32_e64 v139, s[4:5], 0, v9, s[4:5]
	v_add_co_u32_e64 v140, s[4:5], s36, v8
	global_load_dword v196, v[132:133], off
	global_load_dword v198, v[134:135], off
	global_load_dword v200, v[136:137], off
	global_load_dword v204, v[138:139], off
	v_addc_co_u32_e64 v141, s[4:5], 0, v9, s[4:5]
	v_add_co_u32_e64 v142, s[4:5], s37, v8
	v_add_u32_e32 v151, 0x13010, v115
	s_nop 0
	v_addc_co_u32_e64 v143, s[4:5], 0, v9, s[4:5]
	v_add_co_u32_e64 v144, s[4:5], s38, v8
	v_add_u32_e32 v152, 0x14010, v115
	s_nop 0
	v_addc_co_u32_e64 v145, s[4:5], 0, v9, s[4:5]
	global_load_dword v206, v[140:141], off
	global_load_dword v208, v[142:143], off
	global_load_dword v210, v[144:145], off
	v_add_u32_e32 v153, 0x11020, v115
	global_load_dword v112, v[112:113], off
	v_add_u32_e32 v154, 0x12020, v115
	v_add_u32_e32 v158, 0x13020, v115
	v_add_u32_e32 v162, 0x14020, v115
	v_add_u32_e32 v166, 0x11030, v115
	v_add_u32_e32 v170, 0x12030, v115
	v_add_u32_e32 v174, 0x13030, v115
	v_add_u32_e32 v115, 0x14030, v115
	ds_read_b128 v[116:119], v125
	ds_read_b128 v[120:123], v146
	ds_read_b128 v[126:129], v147
	ds_read_b128 v[130:133], v148
	ds_read_b128 v[134:137], v149
	ds_read_b128 v[138:141], v150
	ds_read_b128 v[142:145], v151
	ds_read_b128 v[146:149], v152
	ds_read_b128 v[150:153], v153
	ds_read_b128 v[154:157], v154
	ds_read_b128 v[158:161], v158
	ds_read_b128 v[162:165], v162
	ds_read_b128 v[166:169], v166
	ds_read_b128 v[170:173], v170
	ds_read_b128 v[174:177], v174
	ds_read_b128 v[178:181], v115
	s_waitcnt lgkmcnt(14)
	v_mov_b32_e32 v212, v116
	v_mov_b32_e32 v213, v120
	s_waitcnt lgkmcnt(13)
	v_mov_b32_e32 v214, v126
	s_waitcnt lgkmcnt(12)
	v_mov_b32_e32 v215, v130
	v_mov_b32_e32 v120, v117
	v_mov_b32_e32 v130, v127
	v_mov_b32_e32 v116, v118
	v_mov_b32_e32 v117, v122
	v_mov_b32_e32 v122, v119
	v_mov_b32_e32 v118, v128
	v_mov_b32_e32 v119, v132
	v_mov_b32_e32 v132, v129
	s_waitcnt lgkmcnt(11)
	v_mov_b32_e32 v126, v134
	s_waitcnt lgkmcnt(10)
	v_mov_b32_e32 v127, v138
	v_mov_b32_e32 v138, v135
	s_waitcnt lgkmcnt(9)
	v_mov_b32_e32 v134, v142
	s_waitcnt lgkmcnt(8)
	v_mov_b32_e32 v135, v146
	v_mov_b32_e32 v146, v143
	v_mov_b32_e32 v128, v136
	v_mov_b32_e32 v129, v140
	v_mov_b32_e32 v140, v137
	v_mov_b32_e32 v136, v144
	v_mov_b32_e32 v137, v148
	v_mov_b32_e32 v148, v145
	s_waitcnt lgkmcnt(7)
	v_mov_b32_e32 v142, v150
	s_waitcnt lgkmcnt(6)
	v_mov_b32_e32 v143, v154
	v_mov_b32_e32 v154, v151
	s_waitcnt lgkmcnt(5)
	v_mov_b32_e32 v150, v158
	s_waitcnt lgkmcnt(4)
	v_mov_b32_e32 v151, v162
	v_mov_b32_e32 v162, v159
	v_mov_b32_e32 v144, v152
	v_mov_b32_e32 v145, v156
	v_mov_b32_e32 v156, v153
	v_mov_b32_e32 v152, v160
	v_mov_b32_e32 v153, v164
	v_mov_b32_e32 v164, v161
	s_waitcnt lgkmcnt(3)
	v_mov_b32_e32 v158, v166
	s_waitcnt lgkmcnt(2)
	v_mov_b32_e32 v159, v170
	v_mov_b32_e32 v170, v167
	s_waitcnt lgkmcnt(1)
	v_mov_b32_e32 v166, v174
	s_waitcnt lgkmcnt(0)
	v_mov_b32_e32 v167, v178
	v_mov_b32_e32 v178, v175
	v_mov_b32_e32 v160, v168
	v_mov_b32_e32 v161, v172
	v_mov_b32_e32 v172, v169
	v_mov_b32_e32 v168, v176
	v_mov_b32_e32 v169, v180
	s_add_i32 s39, s39, 64
	v_mov_b32_e32 v180, v177
	v_lshl_add_u64 v[8:9], v[8:9], 0, s[10:11]
	s_cmpk_eq_i32 s39, 0x200
	s_waitcnt vmcnt(0)
	v_pk_fma_f32 v[2:3], v[10:11], v[108:109], v[2:3] op_sel_hi:[0,1,1]
	v_pk_fma_f32 v[4:5], v[10:11], v[110:111], v[4:5] op_sel_hi:[0,1,1]
	v_pk_fma_f32 v[2:3], v[80:81], v[18:19], v[2:3] op_sel_hi:[0,1,1]
	v_pk_fma_f32 v[4:5], v[80:81], v[28:29], v[4:5] op_sel_hi:[0,1,1]
	v_pk_fma_f32 v[2:3], v[82:83], v[14:15], v[2:3] op_sel_hi:[0,1,1]
	v_pk_fma_f32 v[4:5], v[82:83], v[16:17], v[4:5] op_sel_hi:[0,1,1]
	v_pk_fma_f32 v[2:3], v[84:85], v[20:21], v[2:3] op_sel_hi:[0,1,1]
	v_pk_fma_f32 v[4:5], v[84:85], v[30:31], v[4:5] op_sel_hi:[0,1,1]
	v_pk_fma_f32 v[2:3], v[86:87], v[24:25], v[2:3] op_sel_hi:[0,1,1]
	v_pk_fma_f32 v[4:5], v[86:87], v[32:33], v[4:5] op_sel_hi:[0,1,1]
	v_pk_fma_f32 v[2:3], v[88:89], v[36:37], v[2:3] op_sel_hi:[0,1,1]
	v_pk_fma_f32 v[4:5], v[88:89], v[44:45], v[4:5] op_sel_hi:[0,1,1]
	v_pk_fma_f32 v[2:3], v[90:91], v[26:27], v[2:3] op_sel_hi:[0,1,1]
	v_pk_fma_f32 v[4:5], v[90:91], v[34:35], v[4:5] op_sel_hi:[0,1,1]
	v_pk_fma_f32 v[2:3], v[92:93], v[38:39], v[2:3] op_sel_hi:[0,1,1]
	v_pk_fma_f32 v[4:5], v[92:93], v[46:47], v[4:5] op_sel_hi:[0,1,1]
	v_pk_fma_f32 v[2:3], v[12:13], v[40:41], v[2:3] op_sel_hi:[0,1,1]
	v_pk_fma_f32 v[4:5], v[12:13], v[48:49], v[4:5] op_sel_hi:[0,1,1]
	v_pk_fma_f32 v[2:3], v[94:95], v[52:53], v[2:3] op_sel_hi:[0,1,1]
	v_pk_fma_f32 v[4:5], v[94:95], v[60:61], v[4:5] op_sel_hi:[0,1,1]
	v_pk_fma_f32 v[2:3], v[96:97], v[42:43], v[2:3] op_sel_hi:[0,1,1]
	v_pk_fma_f32 v[4:5], v[96:97], v[50:51], v[4:5] op_sel_hi:[0,1,1]
	v_pk_fma_f32 v[2:3], v[98:99], v[54:55], v[2:3] op_sel_hi:[0,1,1]
	v_pk_fma_f32 v[4:5], v[98:99], v[62:63], v[4:5] op_sel_hi:[0,1,1]
	v_pk_fma_f32 v[2:3], v[100:101], v[56:57], v[2:3] op_sel_hi:[0,1,1]
	v_pk_fma_f32 v[4:5], v[100:101], v[64:65], v[4:5] op_sel_hi:[0,1,1]
	v_pk_fma_f32 v[2:3], v[102:103], v[68:69], v[2:3] op_sel_hi:[0,1,1]
	v_pk_fma_f32 v[4:5], v[102:103], v[76:77], v[4:5] op_sel_hi:[0,1,1]
	v_pk_fma_f32 v[2:3], v[104:105], v[58:59], v[2:3] op_sel_hi:[0,1,1]
	v_pk_fma_f32 v[4:5], v[104:105], v[66:67], v[4:5] op_sel_hi:[0,1,1]
	v_pk_fma_f32 v[2:3], v[106:107], v[70:71], v[2:3] op_sel_hi:[0,1,1]
	v_pk_fma_f32 v[4:5], v[106:107], v[78:79], v[4:5] op_sel_hi:[0,1,1]
	v_pk_fma_f32 v[2:3], v[112:113], v[212:213], v[2:3] op_sel_hi:[0,1,1]
	v_pk_fma_f32 v[4:5], v[112:113], v[214:215], v[4:5] op_sel_hi:[0,1,1]
	v_pk_fma_f32 v[2:3], v[182:183], v[120:121], v[2:3] op_sel_hi:[0,1,1]
	v_pk_fma_f32 v[4:5], v[182:183], v[130:131], v[4:5] op_sel_hi:[0,1,1]
	v_pk_fma_f32 v[2:3], v[184:185], v[116:117], v[2:3] op_sel_hi:[0,1,1]
	v_pk_fma_f32 v[4:5], v[184:185], v[118:119], v[4:5] op_sel_hi:[0,1,1]
	v_pk_fma_f32 v[2:3], v[186:187], v[122:123], v[2:3] op_sel_hi:[0,1,1]
	v_pk_fma_f32 v[4:5], v[186:187], v[132:133], v[4:5] op_sel_hi:[0,1,1]
	v_pk_fma_f32 v[2:3], v[188:189], v[126:127], v[2:3] op_sel_hi:[0,1,1]
	v_pk_fma_f32 v[4:5], v[188:189], v[134:135], v[4:5] op_sel_hi:[0,1,1]
	v_pk_fma_f32 v[2:3], v[190:191], v[138:139], v[2:3] op_sel_hi:[0,1,1]
	v_pk_fma_f32 v[4:5], v[190:191], v[146:147], v[4:5] op_sel_hi:[0,1,1]
	v_pk_fma_f32 v[2:3], v[192:193], v[128:129], v[2:3] op_sel_hi:[0,1,1]
	v_pk_fma_f32 v[4:5], v[192:193], v[136:137], v[4:5] op_sel_hi:[0,1,1]
	v_pk_fma_f32 v[2:3], v[194:195], v[140:141], v[2:3] op_sel_hi:[0,1,1]
	v_pk_fma_f32 v[4:5], v[194:195], v[148:149], v[4:5] op_sel_hi:[0,1,1]
	v_pk_fma_f32 v[2:3], v[114:115], v[142:143], v[2:3] op_sel_hi:[0,1,1]
	v_pk_fma_f32 v[4:5], v[114:115], v[150:151], v[4:5] op_sel_hi:[0,1,1]
	v_pk_fma_f32 v[2:3], v[196:197], v[154:155], v[2:3] op_sel_hi:[0,1,1]
	v_pk_fma_f32 v[4:5], v[196:197], v[162:163], v[4:5] op_sel_hi:[0,1,1]
	v_pk_fma_f32 v[2:3], v[198:199], v[144:145], v[2:3] op_sel_hi:[0,1,1]
	v_pk_fma_f32 v[4:5], v[198:199], v[152:153], v[4:5] op_sel_hi:[0,1,1]
	v_pk_fma_f32 v[2:3], v[200:201], v[156:157], v[2:3] op_sel_hi:[0,1,1]
	v_pk_fma_f32 v[4:5], v[200:201], v[164:165], v[4:5] op_sel_hi:[0,1,1]
	v_pk_fma_f32 v[2:3], v[204:205], v[158:159], v[2:3] op_sel_hi:[0,1,1]
	v_pk_fma_f32 v[4:5], v[204:205], v[166:167], v[4:5] op_sel_hi:[0,1,1]
	v_pk_fma_f32 v[2:3], v[206:207], v[170:171], v[2:3] op_sel_hi:[0,1,1]
	v_pk_fma_f32 v[4:5], v[206:207], v[178:179], v[4:5] op_sel_hi:[0,1,1]
	v_pk_fma_f32 v[2:3], v[208:209], v[160:161], v[2:3] op_sel_hi:[0,1,1]
	v_pk_fma_f32 v[4:5], v[208:209], v[168:169], v[4:5] op_sel_hi:[0,1,1]
	v_pk_fma_f32 v[2:3], v[210:211], v[172:173], v[2:3] op_sel_hi:[0,1,1]
	v_pk_fma_f32 v[4:5], v[210:211], v[180:181], v[4:5] op_sel_hi:[0,1,1]
	s_cbranch_scc0 .LBB0_13
	v_lshl_add_u32 v7, v202, 4, 0
	s_movk_i32 s4, 0x100
	v_add_u32_e32 v7, 0x15000, v7
	v_cmp_gt_u32_e32 vcc, s4, v202
	ds_write_b128 v7, v[2:5]
	s_waitcnt lgkmcnt(0)
	s_barrier
	s_and_saveexec_b64 s[4:5], vcc
	s_cbranch_execz .LBB0_16
	s_load_dwordx2 s[10:11], s[0:1], 0x20
	s_and_b64 s[14:15], s[8:9], exec
	s_cselect_b32 s13, 0x1800, 0
	s_add_i32 s13, s6, s13
	v_or_b32_e32 v2, s13, v6
	v_mov_b32_e32 v3, 0
	s_waitcnt lgkmcnt(0)
	v_lshl_add_u64 v[4:5], v[2:3], 2, s[10:11]
	global_load_dword v7, v[4:5], off
	v_lshlrev_b32_e32 v2, 4, v6
	v_lshlrev_b32_e32 v4, 2, v1
	s_add_i32 s10, 0, 0x15000
	v_add3_u32 v2, s10, v2, v4
	s_and_b64 s[8:9], s[8:9], exec
	ds_read2st64_b32 v[4:5], v2 offset1:4
	ds_read2st64_b32 v[8:9], v2 offset0:8 offset1:12
	ds_read2st64_b32 v[10:11], v2 offset0:16 offset1:20
	ds_read2st64_b32 v[12:13], v2 offset0:24 offset1:28
	s_cselect_b32 s8, 4, 0
	v_or_b32_e32 v1, s8, v1
	v_mul_u32_u24_e32 v2, 0x6000, v1
	v_lshl_add_u64 v[14:15], s[28:29], 0, v[2:3]
	v_lshlrev_b32_e32 v2, 2, v6
	v_lshl_add_u64 v[14:15], s[6:7], 2, v[14:15]
	v_lshl_add_u64 v[2:3], v[14:15], 0, v[2:3]
	v_add_co_u32_e32 v2, vcc, 0x3100000, v2
	s_waitcnt vmcnt(0) lgkmcnt(3)
	v_add_f32_e32 v1, v7, v4
	v_add_f32_e32 v1, v1, v5
	s_waitcnt lgkmcnt(2)
	v_add_f32_e32 v1, v1, v8
	v_add_f32_e32 v1, v1, v9
	s_waitcnt lgkmcnt(1)
	v_add_f32_e32 v1, v1, v10
	v_add_f32_e32 v1, v1, v11
	s_waitcnt lgkmcnt(0)
	v_add_f32_e32 v1, v1, v12
	v_add_f32_e32 v1, v1, v13
	v_addc_co_u32_e32 v3, vcc, 0, v3, vcc
	global_store_dword v[2:3], v1, off

.LBB0_204:
	s_or_b64 exec, exec, s[4:5]
	v_mov_b32_e32 v2, v202
	s_waitcnt lgkmcnt(0)
	s_barrier
	s_nop 0
	s_nop 0
	s_nop 0
	s_nop 0
	s_nop 0
	s_nop 0
	s_nop 0
	s_nop 0
	s_nop 0
	s_nop 0
	s_nop 0
	s_nop 0
	s_nop 0
	s_nop 0
	s_nop 0
	s_nop 0
	s_nop 0
	s_nop 0
	s_nop 0
	s_nop 0
	s_nop 0
	s_nop 0
	s_nop 0
	s_nop 0
	s_nop 0
	s_nop 0
	s_nop 0
	s_nop 0
	s_nop 0
	s_nop 0
	s_nop 0
	s_nop 0
	s_nop 0
	s_nop 0
	s_nop 0
	s_nop 0
	s_nop 0
	s_nop 0
	s_nop 0
	s_nop 0
	s_nop 0
	s_nop 0
	s_nop 0
	s_nop 0
	s_nop 0
	s_nop 0
	s_nop 0
	s_nop 0
	s_nop 0
	s_nop 0
	s_nop 0
	s_nop 0
	s_nop 0
	s_nop 0
	s_nop 0
	s_nop 0
	s_nop 0
	s_nop 0
	s_nop 0
	s_nop 0
	v_mbcnt_lo_u32_b32 v1, -1, 0
	v_readfirstlane_b32 s4, v2
	s_ashr_i32 s4, s4, 6
	s_add_i32 s4, s4, s76
	s_cmpk_gt_i32 s4, 0x7fff
	s_cbranch_scc1 .LBB0_207
	s_load_dwordx2 s[6:7], s[0:1], 0x0
	s_load_dwordx2 s[8:9], s[0:1], 0x28
	s_add_u32 s12, s28, 0x3100000
	s_addc_u32 s13, s29, 0
	s_ashr_i32 s5, s4, 31
	s_lshl_b64 s[10:11], s[4:5], 12
	v_and_b32_e32 v21, 63, v2
	s_waitcnt lgkmcnt(0)
	s_add_u32 s10, s6, s10
	s_addc_u32 s11, s7, s11
	v_lshlrev_b32_e32 v18, 4, v21
	global_load_dwordx4 v[2:5], v18, s[10:11] offset:3072
	global_load_dwordx4 v[6:9], v18, s[10:11] offset:2048
	global_load_dwordx4 v[14:17], v18, s[10:11]
	global_load_dwordx4 v[10:13], v18, s[10:11] offset:1024
	v_mbcnt_hi_u32_b32 v25, -1, v1
	v_and_b32_e32 v24, 64, v25
	v_xor_b32_e32 v27, 1, v25
	v_add_u32_e32 v35, 64, v24
	v_xor_b32_e32 v29, 2, v25
	v_lshlrev_b32_e32 v20, 2, v21
	v_cmp_lt_i32_e32 vcc, v27, v35
	v_xor_b32_e32 v31, 4, v25
	v_or_b32_e32 v24, 0x100, v20
	v_or_b32_e32 v26, 0x200, v20
	v_or_b32_e32 v28, 0x300, v20
	v_lshlrev_b32_e32 v30, 2, v20
	v_cndmask_b32_e32 v20, v25, v27, vcc
	v_cmp_lt_i32_e32 vcc, v29, v35
	v_xor_b32_e32 v32, 8, v25
	v_xor_b32_e32 v33, 16, v25
	v_cndmask_b32_e32 v27, v25, v29, vcc
	v_cmp_lt_i32_e32 vcc, v31, v35
	v_xor_b32_e32 v34, 32, v25
	v_mov_b32_e32 v19, 0
	v_cndmask_b32_e32 v29, v25, v31, vcc
	v_cmp_lt_i32_e32 vcc, v32, v35
	v_lshlrev_b32_e32 v31, 2, v24
	s_mov_b64 s[10:11], 0x4000000
	v_cndmask_b32_e32 v37, v25, v32, vcc
	v_cmp_lt_i32_e32 vcc, v33, v35
	v_lshlrev_b32_e32 v32, 2, v26
	v_mov_b32_e32 v23, 0x358637bd
	v_cndmask_b32_e32 v38, v25, v33, vcc
	v_cmp_lt_i32_e32 vcc, v34, v35
	v_lshlrev_b32_e32 v35, 2, v27
	v_lshl_add_u64 v[26:27], s[8:9], 0, v[18:19]
	v_cndmask_b32_e32 v25, v25, v34, vcc
	v_lshlrev_b32_e32 v39, 2, v25
	v_lshl_add_u64 v[24:25], s[6:7], 0, v[18:19]
	s_lshl_b64 s[6:7], s[4:5], 11
	s_add_u32 s6, s28, s6
	v_lshlrev_b32_e32 v18, 3, v21
	s_addc_u32 s7, s29, s7
	s_ashr_i32 s37, s36, 31
	v_lshl_add_u64 v[18:19], s[6:7], 0, v[18:19]
	s_mov_b32 s14, 0x800000
	v_lshlrev_b32_e32 v33, 2, v28
	v_lshlrev_b32_e32 v34, 2, v20
	v_lshlrev_b32_e32 v36, 2, v29
	v_lshlrev_b32_e32 v37, 2, v37
	v_lshlrev_b32_e32 v38, 2, v38
	s_lshl_b64 s[6:7], s[36:37], 11
	v_lshl_add_u64 v[28:29], v[18:19], 0, s[10:11]
	s_waitcnt vmcnt(3)
	v_mov_b32_e32 v18, v2
	v_mov_b32_e32 v19, v3
	v_mov_b32_e32 v20, v4
	v_mov_b32_e32 v21, v5
	s_mov_b32 s98, -1
	global_load_dwordx4 v[104:107], v[26:27], off
	global_load_dwordx4 v[68:71], v[26:27], off offset:1024
	global_load_dwordx4 v[80:83], v[26:27], off offset:2048
	global_load_dwordx4 v[92:95], v[26:27], off offset:3072
